# P0 prologue: the six table-build loads are issued together before the LDS zeroing loop (on top of the P0 wave re-balance)
# baseline (speedup 1.0000x reference)
.LBB0_27:
	s_load_dwordx16 s[52:67], s[0:1], 0x0
	s_load_dwordx16 s[36:51], s[0:1], 0x40
	s_load_dwordx16 s[12:27], s[0:1], 0x80
	s_lshr_b32 s34, s96, 6
	s_cmp_lt_i32 s28, 1
	s_cselect_b64 s[0:1], -1, 0
	s_cmp_gt_i32 s29, 0
	s_cselect_b64 s[4:5], -1, 0
	s_and_b64 s[72:73], s[0:1], s[4:5]
	s_andn2_b64 vcc, exec, s[72:73]
	v_and_b32_e32 v139, 63, v196
	s_cbranch_vccnz .LBB0_106
	s_waitcnt lgkmcnt(0)
	v_lshlrev_b32_e32 v40, 2, v196
	v_mov_b32_e32 v41, 0
	v_lshl_add_u64 v[40:41], s[54:55], 0, v[40:41]
	s_movk_i32 s0, 0x2020
	v_mov_b64_e32 v[42:43], s[56:57]
	s_nop 0
	v_mad_u64_u32 v[42:43], s[8:9], v196, s0, v[42:43]
	s_mov_b64 s[0:1], 0x1800
	v_lshl_add_u64 v[42:43], v[42:43], 0, s[0:1]
	global_load_dword v44, v[40:41], off
	global_load_dwordx4 v[48:51], v[42:43], off
	global_load_dwordx4 v[52:55], v[42:43], off offset:16
	s_mov_b64 s[0:1], 0x800
	v_lshl_add_u64 v[40:41], v[40:41], 0, s[0:1]
	s_mov_b64 s[0:1], 0x404000
	v_lshl_add_u64 v[42:43], v[42:43], 0, s[0:1]
	global_load_dword v56, v[40:41], off
	global_load_dwordx4 v[60:63], v[42:43], off
	global_load_dwordx4 v[64:67], v[42:43], off offset:16
	v_add_u32_e32 v4, 0xfffffe00, v196
	s_mov_b64 s[0:1], 0
	v_mov_b32_e32 v0, 0
	s_movk_i32 s4, 0x7dff
	v_mov_b32_e32 v1, v4

.LBB0_31:
	s_waitcnt vmcnt(0)
	v_mov_b32_e32 v7, v44
	v_mov_b32_e32 v8, v48
	v_mov_b32_e32 v9, v49
	v_mov_b32_e32 v10, v50
	v_mov_b32_e32 v11, v51
	v_mov_b32_e32 v12, v52
	v_mov_b32_e32 v13, v53
	v_mov_b32_e32 v14, v54
	v_mov_b32_e32 v15, v55
	v_mov_b32_e32 v44, v56
	v_mov_b32_e32 v48, v60
	v_mov_b32_e32 v49, v61
	v_mov_b32_e32 v50, v62
	v_mov_b32_e32 v51, v63
	v_mov_b32_e32 v52, v64
	v_mov_b32_e32 v53, v65
	v_mov_b32_e32 v54, v66
	v_mov_b32_e32 v55, v67
	v_and_b32_e32 v16, 14, v5
	v_and_or_b32 v16, v6, s8, v16
	v_add_co_u32_e32 v4, vcc, 0x200, v4
	v_add_u32_e32 v16, 0, v16
	s_xor_b64 s[10:11], vcc, -1
	s_and_b64 s[10:11], exec, s[10:11]
	v_add_u32_e32 v5, 0x400, v5
	v_lshl_add_u64 v[0:1], v[0:1], 0, s[4:5]
	v_lshl_add_u64 v[2:3], v[2:3], 0, s[6:7]
	v_add_u32_e32 v6, 0x4000, v6
	s_or_b64 s[0:1], s[10:11], s[0:1]
	s_waitcnt vmcnt(1)
	v_mul_f32_e32 v17, v7, v8
	v_mul_f32_e32 v18, v7, v9
	v_mul_f32_e32 v19, v7, v10
	v_mul_f32_e32 v20, v7, v11
	s_waitcnt vmcnt(0)
	v_mul_f32_e32 v21, v7, v12
	v_mul_f32_e32 v22, v7, v13
	v_mul_f32_e32 v23, v7, v14
	v_mul_f32_e32 v24, v7, v15
	v_bfe_u32 v25, v17, 16, 1
	v_bfe_u32 v26, v18, 16, 1
	v_bfe_u32 v27, v19, 16, 1
	v_bfe_u32 v28, v20, 16, 1
	v_bfe_u32 v29, v21, 16, 1
	v_bfe_u32 v30, v22, 16, 1
	v_bfe_u32 v31, v23, 16, 1
	v_bfe_u32 v32, v24, 16, 1
	v_add3_u32 v17, v17, v25, s9
	v_add3_u32 v18, v18, v26, s9
	v_add3_u32 v19, v19, v27, s9
	v_add3_u32 v20, v20, v28, s9
	v_add3_u32 v21, v21, v29, s9
	v_add3_u32 v22, v22, v30, s9
	v_add3_u32 v23, v23, v31, s9
	v_add3_u32 v24, v24, v32, s9
	v_and_b32_e32 v25, 0xffff0000, v17
	ds_write_b16_d16_hi v16, v17
	v_and_b32_e32 v17, 0xffff0000, v18
	ds_write_b16_d16_hi v16, v18 offset:16
	v_and_b32_e32 v18, 0xffff0000, v19
	ds_write_b16_d16_hi v16, v19 offset:32
	v_and_b32_e32 v19, 0xffff0000, v20
	ds_write_b16_d16_hi v16, v20 offset:48
	v_and_b32_e32 v20, 0xffff0000, v21
	ds_write_b16_d16_hi v16, v21 offset:64
	v_and_b32_e32 v21, 0xffff0000, v22
	ds_write_b16_d16_hi v16, v22 offset:80
	v_and_b32_e32 v22, 0xffff0000, v23
	ds_write_b16_d16_hi v16, v23 offset:96
	v_and_b32_e32 v23, 0xffff0000, v24
	v_fma_f32 v8, v7, v8, -v25
	v_fma_f32 v9, v7, v9, -v17
	v_fma_f32 v10, v7, v10, -v18
	v_fma_f32 v11, v7, v11, -v19
	v_fma_f32 v12, v7, v12, -v20
	v_fma_f32 v13, v7, v13, -v21
	v_fma_f32 v14, v7, v14, -v22
	v_fma_f32 v7, v7, v15, -v23
	v_bfe_u32 v15, v8, 16, 1
	v_bfe_u32 v17, v9, 16, 1
	v_bfe_u32 v18, v10, 16, 1
	v_bfe_u32 v19, v11, 16, 1
	v_bfe_u32 v20, v12, 16, 1
	v_bfe_u32 v21, v13, 16, 1
	v_bfe_u32 v22, v14, 16, 1
	v_bfe_u32 v23, v7, 16, 1
	v_add3_u32 v8, v8, v15, s9
	ds_write_b16_d16_hi v16, v24 offset:112
	v_add3_u32 v9, v9, v17, s9
	v_add3_u32 v10, v10, v18, s9
	v_add3_u32 v11, v11, v19, s9
	v_add3_u32 v12, v12, v20, s9
	v_add3_u32 v13, v13, v21, s9
	v_add3_u32 v14, v14, v22, s9
	v_add3_u32 v7, v7, v23, s9
	ds_write_b16_d16_hi v16, v8 offset:32768
	ds_write_b16_d16_hi v16, v9 offset:32784
	ds_write_b16_d16_hi v16, v10 offset:32800
	ds_write_b16_d16_hi v16, v11 offset:32816
	ds_write_b16_d16_hi v16, v12 offset:32832
	ds_write_b16_d16_hi v16, v13 offset:32848
	ds_write_b16_d16_hi v16, v14 offset:32864
	ds_write_b16_d16_hi v16, v7 offset:32880
	s_andn2_b64 exec, exec, s[0:1]
	s_cbranch_execnz .LBB0_31
	v_writelane_b32 v255, s33, 0
	v_writelane_b32 v255, s95, 1
	v_writelane_b32 v255, s94, 2
	v_writelane_b32 v255, s92, 3
	s_nop 1
	v_writelane_b32 v255, s93, 4
	s_or_b64 exec, exec, s[0:1]
	s_lshl_b32 s1, s3, 2
	s_lshr_b32 s0, s96, 7
	s_add_i32 s74, s1, s0
	s_cmpk_gt_i32 s74, 0x3ff
	v_and_b32_e32 v96, 15, v196
	s_waitcnt lgkmcnt(0)
	s_barrier
	s_cbranch_scc1 .LBB0_49
	v_mbcnt_lo_u32_b32 v0, -1, 0
	v_mbcnt_hi_u32_b32 v0, -1, v0
	v_and_b32_e32 v4, 64, v0
	v_xor_b32_e32 v3, 16, v0
	v_add_u32_e32 v5, 64, v4
	v_cmp_lt_i32_e32 vcc, v3, v5
	s_bfe_u32 s10, s96, 0x10006
	s_and_b32 s1, 64, s96
	v_cndmask_b32_e32 v3, v0, v3, vcc
	v_lshlrev_b32_e32 v97, 2, v3
	v_xor_b32_e32 v3, 32, v0
	v_cmp_lt_i32_e32 vcc, v3, v5
	s_cmp_eq_u32 s10, 0
	s_cselect_b64 s[76:77], -1, 0
	v_cndmask_b32_e32 v0, v0, v3, vcc
	s_cmp_lg_u32 s1, 0
	v_lshlrev_b32_e32 v3, 4, v139
	v_lshlrev_b32_e32 v2, 4, v96
	s_cselect_b64 s[6:7], -1, 0
	s_lshl_b32 s8, s10, 14
	v_and_b32_e32 v3, 0x300, v3
	s_ashr_i32 s75, s74, 31
	v_or3_b32 v6, s8, v3, v2
	v_lshlrev_b32_e32 v2, 2, v4
	s_lshl_b64 s[8:9], s[74:75], 15
	v_and_or_b32 v133, v139, 48, v2
	v_lshl_or_b32 v2, v96, 11, s8
	s_lshl_b32 s8, s10, 10
	v_and_b32_e32 v3, 48, v196
	v_or3_b32 v2, v2, s8, v3
	v_mov_b32_e32 v3, s9
	v_lshlrev_b32_e32 v132, 2, v0
	v_lshl_or_b32 v0, s0, 6, v139
	v_bfe_u32 v4, v196, 4, 2
	v_lshl_add_u64 v[2:3], s[70:71], 0, v[2:3]
	s_mov_b64 s[8:9], 0x2000200
	v_mul_lo_u32 v5, v0, 20
	v_lshlrev_b32_e32 v0, 2, v96
	v_lshl_add_u64 v[100:101], v[2:3], 0, s[8:9]
	s_lshl_b64 s[8:9], s[74:75], 9
	v_lshlrev_b32_e32 v2, 7, v4
	v_or3_b32 v2, s8, v2, v0
	v_mov_b32_e32 v3, s9
	v_lshl_add_u64 v[2:3], s[70:71], 0, v[2:3]
	s_mov_b64 s[8:9], 0x1900040
	v_lshl_add_u64 v[102:103], v[2:3], 0, s[8:9]
	s_lshl_b64 s[8:9], s[74:75], 16
	v_mov_b32_e32 v1, 0
	v_lshl_or_b32 v2, v96, 12, s8
	s_lshl_b32 s8, s10, 11
	v_lshlrev_b32_e32 v3, 5, v4
	v_lshl_add_u64 v[98:99], s[58:59], 0, v[0:1]
	s_lshl_b32 s58, s30, 2
	v_or3_b32 v2, v2, s8, v3
	v_mov_b32_e32 v3, s9
	s_ashr_i32 s59, s58, 31
	v_lshl_add_u64 v[2:3], s[52:53], 0, v[2:3]
	s_mov_b64 s[8:9], 0x400
	s_lshl_b64 s[78:79], s[58:59], 15
	s_lshl_b64 s[80:81], s[58:59], 9
	v_lshl_add_u64 v[104:105], v[2:3], 0, s[8:9]
	s_lshl_b64 s[52:53], s[58:59], 16
	s_lshl_b64 s[8:9], s[74:75], 6
	s_add_u32 s8, s70, s8
	s_addc_u32 s9, s71, s9
	v_lshl_add_u64 v[0:1], s[8:9], 0, v[0:1]
	s_mov_b64 s[8:9], 0x1a60000
	v_lshl_add_u64 v[106:107], v[0:1], 0, s[8:9]
	v_cndmask_b32_e64 v0, 0, 1, s[6:7]
	v_cmp_gt_u32_e64 s[0:1], 16, v139
	v_cmp_gt_u32_e64 s[4:5], 8, v96
	v_or_b32_e32 v134, 4, v133
	v_or_b32_e32 v135, 8, v133
	v_or_b32_e32 v136, 12, v133
	s_lshl_b64 s[82:83], s[58:59], 6
	s_movk_i32 s35, 0x7fff
	s_mov_b32 s59, 0xffff0000
	v_add_u32_e32 v137, 0, v6
	v_mov_b32_e32 v138, 0x358637bd
	s_mov_b32 s75, 0xf800000
	v_mov_b32_e32 v140, 0x260
	s_mov_b32 s84, 0xbfb8aa3b
	s_mov_b32 s85, 0xb2a5705f
	s_mov_b32 s89, 0x42ce8ed0
	s_mov_b32 s90, 0xc2b17218
	s_mov_b32 s91, 0x7f800000
	s_mov_b32 s92, 0x3f2aaaab
	v_mov_b32_e32 v141, 0x3ecc95a3
	s_mov_b32 s93, 0x3f317218
	s_mov_b32 s94, 0x33800000
	v_mov_b32_e32 v142, 1
	v_cmp_ne_u32_e64 s[6:7], 1, v0
	v_add_u32_e32 v143, 0, v5
	v_mov_b32_e32 v144, 0x7f800000
	v_mov_b32_e32 v108, 0x3f317218
	s_branch .LBB0_36
